# GEMM phases without the static s_setprio raise for the second-arriving waves (nowait flag store kept)
# speedup vs baseline: 1.0034x; 1.0034x over previous
.LBB0_191:
	s_andn2_b64 vcc, exec, s[2:3]
	s_cbranch_vccnz .LBB0_247
	v_readlane_b32 s10, v164, 0
	v_readlane_b32 s11, v162, 14
	v_readlane_b32 s16, v163, 15
	v_readlane_b32 s17, v163, 16
	v_readlane_b32 s18, v163, 5
	v_readlane_b32 s19, v163, 6
	s_mul_i32 s4, s34, 0x1600000
	s_add_u32 s18, s18, s4
	s_addc_u32 s19, s19, 0
	s_movk_i32 s42, 0x800
	v_and_b32_e32 v220, 63, v128
	v_lshrrev_b32_e32 v221, 6, v128
	v_and_b32_e32 v222, 15, v220
	v_lshrrev_b32_e32 v223, 4, v220
	v_readfirstlane_b32 s40, v221
	v_bfe_u32 v224, v222, 1, 3
	s_lshl_b32 s13, s40, 10
	s_and_b32 s36, s40, 1
	s_lshr_b32 s35, s40, 1
	v_xor_b32_e32 v225, v223, v224
	v_lshlrev_b32_e32 v225, 4, v225
	s_mul_i32 s4, s35, 0x50
	v_add_u32_e32 v226, s4, v222
	v_lshl_add_u32 v116, v226, 7, v225
	v_xor_b32_e32 v118, 64, v116
	s_lshl_b32 s4, s36, 6
	v_add_u32_e32 v227, s4, v222
	v_lshl_add_u32 v119, v227, 7, v225
	v_xor_b32_e32 v160, 64, v119
	v_and_b32_e32 v228, 7, v220
	v_lshrrev_b32_e32 v229, 3, v220
	v_xor_b32_e32 v230, v228, v223
	s_lshl_b32 s4, s36, 2
	v_xor_b32_e32 v230, s4, v230
	v_lshlrev_b32_e32 v230, 4, v230
	s_lshl_b32 s4, s40, 3
	v_add_u32_e32 v231, s4, v229
	v_mad_u32_u24 v161, v231, s42, v230
	v_bfe_u32 v232, v231, 2, 2
	v_and_b32_e32 v233, 3, v231
	v_lshrrev_b32_e32 v234, 4, v231
	v_lshl_add_u32 v232, v232, 3, v233
	s_movk_i32 s4, 0xb00
	v_mad_u32_u24 v232, v234, s4, v232
	v_mad_u32_u24 v165, v232, s42, v230
	v_mul_u32_u24_e32 v167, 0x1600, v226
	v_lshl_add_u32 v167, v223, 4, v167
	s_lshl_b32 s4, s36, 6
	v_add_u32_e32 v167, s4, v167
	s_movk_i32 s50, 0x580
	s_sub_u32 s51, s50, 1
	s_cmp_ge_u32 s10, s50
	s_cbranch_scc1 .Lggu0_done
	s_and_b32 s4, s10, 7
	s_lshl_b32 s4, s4, 3
	s_bfe_u32 s32, s10, 0x30003
	s_or_b32 s4, s4, s32
	s_mul_i32 s4, s4, 0x50000
	s_add_u32 s2, s16, s4
	s_addc_u32 s3, s17, 0
	s_lshr_b32 s4, s10, 6
	s_mul_i32 s4, s4, 0x40000
	s_add_u32 s6, s18, s4
	s_addc_u32 s7, s19, 0
	s_add_u32 m0, s13, 0x0
	s_nop 0
	global_load_lds_dwordx4 v161, s[2:3] sc1
	s_add_u32 m0, s13, 0x1000
	v_add_u32_e32 v166, 0x10000, v161
	global_load_lds_dwordx4 v166, s[2:3] sc1
	s_add_u32 m0, s13, 0x2000
	v_add_u32_e32 v166, 0x20000, v161
	global_load_lds_dwordx4 v166, s[2:3] sc1
	s_add_u32 m0, s13, 0x3000
	v_add_u32_e32 v166, 0x30000, v161
	global_load_lds_dwordx4 v166, s[2:3] sc1
	s_add_u32 m0, s13, 0x4000
	v_add_u32_e32 v166, 0x40000, v161
	global_load_lds_dwordx4 v166, s[2:3] sc1
	s_add_u32 m0, s13, 0x5000
	s_nop 0
	global_load_lds_dwordx4 v165, s[6:7]
	s_add_u32 m0, s13, 0x6000
	v_add_u32_e32 v166, 0x2000, v165
	global_load_lds_dwordx4 v166, s[6:7]
	s_add_u32 m0, s13, 0x7000
	v_add_u32_e32 v166, 0x10000, v165
	global_load_lds_dwordx4 v166, s[6:7]
	s_add_u32 m0, s13, 0x8000
	v_add_u32_e32 v166, 0x12000, v165
	global_load_lds_dwordx4 v166, s[6:7]
	s_add_u32 s24, s6, 0x20000
	s_addc_u32 s25, s7, 0
	s_add_u32 s2, s2, 0x80
	s_addc_u32 s3, s3, 0
	s_add_u32 s6, s6, 0x80
	s_addc_u32 s7, s7, 0
	s_mov_b32 s48, 0

.LBB0_249:
	s_andn2_b64 vcc, exec, s[2:3]
	s_mul_i32 s2, s34, 0x580000
	v_writelane_b32 v162, s2, 39
	s_nop 1
	v_writelane_b32 v162, s3, 40
	s_nop 0
	v_readlane_b32 s2, v162, 6
	v_readlane_b32 s3, v162, 7
	s_nop 1
	v_cndmask_b32_e64 v0, 0, 1, s[2:3]
	v_cmp_ne_u32_e64 s[2:3], 1, v0
	s_nop 1
	v_writelane_b32 v162, s2, 41
	s_nop 1
	v_writelane_b32 v162, s3, 42
	s_cbranch_vccnz .LBB0_317
	v_readlane_b32 s10, v164, 0
	v_readlane_b32 s11, v162, 14
	s_mov_b32 s16, s76
	s_mov_b32 s17, s77
	v_readlane_b32 s18, v163, 7
	v_readlane_b32 s19, v163, 8
	s_mul_i32 s4, s34, 0xb00000
	s_add_u32 s18, s18, s4
	s_addc_u32 s19, s19, 0
	s_movk_i32 s42, 0x1600
	v_and_b32_e32 v220, 63, v128
	v_lshrrev_b32_e32 v221, 6, v128
	v_and_b32_e32 v222, 15, v220
	v_lshrrev_b32_e32 v223, 4, v220
	v_readfirstlane_b32 s40, v221
	v_bfe_u32 v224, v222, 1, 3
	s_lshl_b32 s13, s40, 10
	s_and_b32 s36, s40, 1
	s_lshr_b32 s35, s40, 1
	v_xor_b32_e32 v225, v223, v224
	v_lshlrev_b32_e32 v225, 4, v225
	s_mul_i32 s4, s35, 0x50
	v_add_u32_e32 v226, s4, v222
	v_lshl_add_u32 v204, v226, 7, v225
	v_xor_b32_e32 v205, 64, v204
	s_lshl_b32 s4, s36, 6
	v_add_u32_e32 v227, s4, v222
	v_lshl_add_u32 v206, v227, 7, v225
	v_xor_b32_e32 v207, 64, v206
	v_and_b32_e32 v228, 7, v220
	v_lshrrev_b32_e32 v229, 3, v220
	v_xor_b32_e32 v230, v228, v223
	s_lshl_b32 s4, s36, 2
	v_xor_b32_e32 v230, s4, v230
	v_lshlrev_b32_e32 v230, 4, v230
	s_lshl_b32 s4, s40, 3
	v_add_u32_e32 v231, s4, v229
	v_mad_u32_u24 v208, v231, s42, v230
	v_add_u32_e32 v209, 0x2c000, v208
	v_add_u32_e32 v210, 0x58000, v208
	v_add_u32_e32 v211, 0x84000, v208
	v_add_u32_e32 v212, 0xb0000, v208
	v_bfe_u32 v232, v231, 2, 2
	v_and_b32_e32 v233, 3, v231
	v_lshrrev_b32_e32 v234, 4, v231
	v_lshl_add_u32 v232, v232, 3, v233
	v_lshl_add_u32 v232, v234, 2, v232
	v_mad_u32_u24 v213, v232, s42, v230
	v_add_u32_e32 v214, 0x2c000, v213
	v_add_u32_e32 v215, 0x58000, v213
	v_add_u32_e32 v216, 0x84000, v213
	v_lshlrev_b32_e32 v217, 11, v226
	v_lshl_add_u32 v217, v223, 4, v217
	s_lshl_b32 s4, s36, 7
	v_add_u32_e32 v217, s4, v217
	s_cmp_ge_u32 s10, 0x200
	s_cbranch_scc1 .Lgdn0_done
	s_and_b32 s4, s10, 7
	s_lshl_b32 s4, s4, 3
	s_bfe_u32 s32, s10, 0x30003
	s_or_b32 s4, s4, s32
	s_mul_i32 s4, s4, 0xdc000
	s_add_u32 s2, s16, s4
	s_addc_u32 s3, s17, 0
	s_lshr_b32 s4, s10, 6
	s_mul_i32 s4, s4, 0xb0000
	s_add_u32 s6, s18, s4
	s_addc_u32 s7, s19, 0
	s_add_u32 m0, s13, 0x0
	s_nop 0
	global_load_lds_dwordx4 v208, s[2:3] sc1
	s_add_u32 m0, s13, 0x1000
	s_nop 0
	global_load_lds_dwordx4 v209, s[2:3] sc1
	s_add_u32 m0, s13, 0x2000
	s_nop 0
	global_load_lds_dwordx4 v210, s[2:3] sc1
	s_add_u32 m0, s13, 0x3000
	s_nop 0
	global_load_lds_dwordx4 v211, s[2:3] sc1
	s_add_u32 m0, s13, 0x4000
	s_nop 0
	global_load_lds_dwordx4 v212, s[2:3] sc1
	s_add_u32 m0, s13, 0x5000
	s_nop 0
	global_load_lds_dwordx4 v213, s[6:7]
	s_add_u32 m0, s13, 0x6000
	s_nop 0
	global_load_lds_dwordx4 v214, s[6:7]
	s_add_u32 m0, s13, 0x7000
	s_nop 0
	global_load_lds_dwordx4 v215, s[6:7]
	s_add_u32 m0, s13, 0x8000
	s_nop 0
	global_load_lds_dwordx4 v216, s[6:7]
	s_add_u32 s2, s2, 0x80
	s_addc_u32 s3, s3, 0
	s_add_u32 s6, s6, 0x80
	s_addc_u32 s7, s7, 0

.Lgdn0_done:
.LBB0_267:
	s_mul_i32 s2, s34, 12
	v_readlane_b32 s20, v162, 12
	s_add_i32 s35, s2, 4
	v_readlane_b32 s21, v162, 13
	s_cmp_ge_i32 s35, s21
	v_readlane_b32 s22, v162, 14
	v_readlane_b32 s23, v162, 15
	s_cbranch_scc1 .LBB0_317
	s_waitcnt vmcnt(0)
	v_readlane_b32 s4, v163, 17
	v_readlane_b32 s5, v163, 18
	s_barrier
	v_readlane_b32 s21, v162, 62
	s_nop 1
	s_cmp_eq_u32 s21, 1
	s_cbranch_scc1 .Lxb1_noinv
	v_lshrrev_b32_e32 v0, 6, v128
	v_readfirstlane_b32 s20, v0
	s_cmp_lg_u32 s20, 1
	s_cbranch_scc1 .Lxb1_ninv
	buffer_inv sc1

.LBB0_375:
	s_andn2_b64 vcc, exec, s[2:3]
	s_cbranch_vccnz .LBB0_521
	v_readlane_b32 s10, v164, 0
	v_readlane_b32 s11, v162, 14
	v_readlane_b32 s16, v163, 15
	v_readlane_b32 s17, v163, 16
	v_readlane_b32 s18, v163, 9
	v_readlane_b32 s19, v163, 10
	s_mul_i32 s4, s34, 0x600000
	s_add_u32 s18, s18, s4
	s_addc_u32 s19, s19, 0
	s_movk_i32 s42, 0x800
	v_and_b32_e32 v220, 63, v128
	v_lshrrev_b32_e32 v221, 6, v128
	v_and_b32_e32 v222, 15, v220
	v_lshrrev_b32_e32 v223, 4, v220
	v_readfirstlane_b32 s40, v221
	v_bfe_u32 v224, v222, 1, 3
	s_lshl_b32 s13, s40, 10
	s_and_b32 s36, s40, 1
	s_lshr_b32 s35, s40, 1
	v_xor_b32_e32 v225, v223, v224
	v_lshlrev_b32_e32 v225, 4, v225
	s_mul_i32 s4, s35, 0x50
	v_add_u32_e32 v226, s4, v222
	v_lshl_add_u32 v204, v226, 7, v225
	v_xor_b32_e32 v205, 64, v204
	s_lshl_b32 s4, s36, 6
	v_add_u32_e32 v227, s4, v222
	v_lshl_add_u32 v206, v227, 7, v225
	v_xor_b32_e32 v207, 64, v206
	v_and_b32_e32 v228, 7, v220
	v_lshrrev_b32_e32 v229, 3, v220
	v_xor_b32_e32 v230, v228, v223
	s_lshl_b32 s4, s36, 2
	v_xor_b32_e32 v230, s4, v230
	v_lshlrev_b32_e32 v230, 4, v230
	s_lshl_b32 s4, s40, 3
	v_add_u32_e32 v231, s4, v229
	v_mad_u32_u24 v208, v231, s42, v230
	v_add_u32_e32 v209, 0x10000, v208
	v_add_u32_e32 v210, 0x20000, v208
	v_add_u32_e32 v211, 0x30000, v208
	v_add_u32_e32 v212, 0x40000, v208
	v_bfe_u32 v232, v231, 2, 2
	v_and_b32_e32 v233, 3, v231
	v_lshrrev_b32_e32 v234, 4, v231
	v_lshl_add_u32 v232, v232, 3, v233
	v_lshl_add_u32 v232, v234, 2, v232
	v_mad_u32_u24 v213, v232, s42, v230
	v_add_u32_e32 v214, 0x10000, v213
	v_add_u32_e32 v215, 0x20000, v213
	v_add_u32_e32 v216, 0x30000, v213
	v_lshlrev_b32_e32 v217, 10, v226
	v_lshl_add_u32 v217, v223, 4, v217
	v_mul_u32_u24_e32 v218, 0x2f00, v226
	v_lshl_add_u32 v218, v223, 5, v218
	s_cmp_ge_u32 s10, 0x600
	s_cbranch_scc1 .Lgzin_done
	s_and_b32 s4, s10, 7
	s_lshl_b32 s4, s4, 3
	s_bfe_u32 s32, s10, 0x30003
	s_or_b32 s4, s4, s32
	s_mul_i32 s4, s4, 0x50000
	s_add_u32 s2, s16, s4
	s_addc_u32 s3, s17, 0
	s_lshr_b32 s4, s10, 6
	s_mul_i32 s4, s4, 0x40000
	s_add_u32 s6, s18, s4
	s_addc_u32 s7, s19, 0
	s_add_u32 m0, s13, 0x0
	s_nop 0
	global_load_lds_dwordx4 v208, s[2:3] sc1
	s_add_u32 m0, s13, 0x1000
	s_nop 0
	global_load_lds_dwordx4 v209, s[2:3] sc1
	s_add_u32 m0, s13, 0x2000
	s_nop 0
	global_load_lds_dwordx4 v210, s[2:3] sc1
	s_add_u32 m0, s13, 0x3000
	s_nop 0
	global_load_lds_dwordx4 v211, s[2:3] sc1
	s_add_u32 m0, s13, 0x4000
	s_nop 0
	global_load_lds_dwordx4 v212, s[2:3] sc1
	s_add_u32 m0, s13, 0x5000
	s_nop 0
	global_load_lds_dwordx4 v213, s[6:7]
	s_add_u32 m0, s13, 0x6000
	s_nop 0
	global_load_lds_dwordx4 v214, s[6:7]
	s_add_u32 m0, s13, 0x7000
	s_nop 0
	global_load_lds_dwordx4 v215, s[6:7]
	s_add_u32 m0, s13, 0x8000
	s_nop 0
	global_load_lds_dwordx4 v216, s[6:7]
	s_add_u32 s2, s2, 0x80
	s_addc_u32 s3, s3, 0
	s_add_u32 s6, s6, 0x80
	s_addc_u32 s7, s7, 0

.Lgzin_done:
.LBB0_471:
	s_mul_i32 s2, s34, 12
	v_readlane_b32 s20, v162, 12
	s_add_i32 s35, s2, 6
	v_readlane_b32 s21, v162, 13
	s_cmp_ge_i32 s35, s21
	v_readlane_b32 s22, v162, 14
	v_readlane_b32 s23, v162, 15
	s_cbranch_scc1 .LBB0_521
	s_waitcnt vmcnt(0)
	v_readlane_b32 s4, v163, 17
	v_readlane_b32 s5, v163, 18
	s_barrier
	v_readlane_b32 s21, v162, 62
	s_nop 1
	s_cmp_eq_u32 s21, 1
	s_cbranch_scc1 .Lxb3_noinv
	v_lshrrev_b32_e32 v0, 6, v128
	v_readfirstlane_b32 s20, v0
	s_cmp_lg_u32 s20, 1
	s_cbranch_scc1 .Lxb3_ninv
	buffer_inv sc1

.LBB0_859:
	s_andn2_b64 vcc, exec, s[2:3]
	s_cbranch_vccnz .LBB0_927
	v_readlane_b32 s10, v164, 0
	v_readlane_b32 s11, v162, 14
	s_mov_b32 s16, s80
	s_mov_b32 s17, s81
	v_readlane_b32 s18, v163, 11
	v_readlane_b32 s19, v163, 12
	s_mul_i32 s4, s34, 0x200000
	s_add_u32 s18, s18, s4
	s_addc_u32 s19, s19, 0
	s_movk_i32 s42, 0x800
	v_and_b32_e32 v220, 63, v128
	v_lshrrev_b32_e32 v221, 6, v128
	v_and_b32_e32 v222, 15, v220
	v_lshrrev_b32_e32 v223, 4, v220
	v_readfirstlane_b32 s40, v221
	v_bfe_u32 v224, v222, 1, 3
	s_lshl_b32 s13, s40, 10
	s_and_b32 s36, s40, 1
	s_lshr_b32 s35, s40, 1
	v_xor_b32_e32 v225, v223, v224
	v_lshlrev_b32_e32 v225, 4, v225
	s_mul_i32 s4, s35, 0x50
	v_add_u32_e32 v226, s4, v222
	v_lshl_add_u32 v204, v226, 7, v225
	v_xor_b32_e32 v205, 64, v204
	s_lshl_b32 s4, s36, 6
	v_add_u32_e32 v227, s4, v222
	v_lshl_add_u32 v206, v227, 7, v225
	v_xor_b32_e32 v207, 64, v206
	v_and_b32_e32 v228, 7, v220
	v_lshrrev_b32_e32 v229, 3, v220
	v_xor_b32_e32 v230, v228, v223
	s_lshl_b32 s4, s36, 2
	v_xor_b32_e32 v230, s4, v230
	v_lshlrev_b32_e32 v230, 4, v230
	s_lshl_b32 s4, s40, 3
	v_add_u32_e32 v231, s4, v229
	v_mad_u32_u24 v208, v231, s42, v230
	v_add_u32_e32 v209, 0x10000, v208
	v_add_u32_e32 v210, 0x20000, v208
	v_add_u32_e32 v211, 0x30000, v208
	v_add_u32_e32 v212, 0x40000, v208
	v_bfe_u32 v232, v231, 2, 2
	v_and_b32_e32 v233, 3, v231
	v_lshrrev_b32_e32 v234, 4, v231
	v_lshl_add_u32 v232, v232, 3, v233
	v_lshl_add_u32 v232, v234, 2, v232
	v_mad_u32_u24 v213, v232, s42, v230
	v_add_u32_e32 v214, 0x10000, v213
	v_add_u32_e32 v215, 0x20000, v213
	v_add_u32_e32 v216, 0x30000, v213
	v_lshlrev_b32_e32 v217, 11, v226
	v_lshl_add_u32 v217, v223, 4, v217
	s_lshl_b32 s4, s36, 7
	v_add_u32_e32 v217, s4, v217
	s_cmp_ge_u32 s10, 0x200
	s_cbranch_scc1 .Lgout_done
	s_and_b32 s4, s10, 7
	s_lshl_b32 s4, s4, 3
	s_bfe_u32 s32, s10, 0x30003
	s_or_b32 s4, s4, s32
	s_mul_i32 s4, s4, 0x50000
	s_add_u32 s2, s16, s4
	s_addc_u32 s3, s17, 0
	s_lshr_b32 s4, s10, 6
	s_mul_i32 s4, s4, 0x40000
	s_add_u32 s6, s18, s4
	s_addc_u32 s7, s19, 0
	s_add_u32 m0, s13, 0x0
	s_nop 0
	global_load_lds_dwordx4 v208, s[2:3] sc1
	s_add_u32 m0, s13, 0x1000
	s_nop 0
	global_load_lds_dwordx4 v209, s[2:3] sc1
	s_add_u32 m0, s13, 0x2000
	s_nop 0
	global_load_lds_dwordx4 v210, s[2:3] sc1
	s_add_u32 m0, s13, 0x3000
	s_nop 0
	global_load_lds_dwordx4 v211, s[2:3] sc1
	s_add_u32 m0, s13, 0x4000
	s_nop 0
	global_load_lds_dwordx4 v212, s[2:3] sc1
	s_add_u32 m0, s13, 0x5000
	s_nop 0
	global_load_lds_dwordx4 v213, s[6:7]
	s_add_u32 m0, s13, 0x6000
	s_nop 0
	global_load_lds_dwordx4 v214, s[6:7]
	s_add_u32 m0, s13, 0x7000
	s_nop 0
	global_load_lds_dwordx4 v215, s[6:7]
	s_add_u32 m0, s13, 0x8000
	s_nop 0
	global_load_lds_dwordx4 v216, s[6:7]
	s_add_u32 s2, s2, 0x80
	s_addc_u32 s3, s3, 0
	s_add_u32 s6, s6, 0x80
	s_addc_u32 s7, s7, 0

.Lgout_done:
.LBB0_877:
	v_readlane_b32 s2, v162, 36
	v_readlane_b32 s20, v162, 12
	s_add_i32 s35, s2, 10
	v_readlane_b32 s21, v162, 13
	s_cmp_ge_i32 s35, s21
	v_readlane_b32 s22, v162, 14
	v_readlane_b32 s23, v162, 15
	s_cbranch_scc1 .LBB0_927
	s_waitcnt vmcnt(0)
	v_readlane_b32 s4, v163, 17
	v_readlane_b32 s5, v163, 18
	s_barrier
	v_readlane_b32 s21, v162, 62
	s_nop 1
	s_cmp_eq_u32 s21, 1
	s_cbranch_scc1 .Lxb7_noinv
	v_lshrrev_b32_e32 v0, 6, v128
	v_readfirstlane_b32 s20, v0
	s_cmp_lg_u32 s20, 1
	s_cbranch_scc1 .Lxb7_ninv
	buffer_inv sc1

.LBB0_985:
	s_andn2_b64 vcc, exec, s[2:3]
	s_cbranch_vccnz .LBB0_1041
	v_readlane_b32 s10, v164, 0
	v_readlane_b32 s11, v162, 14
	v_readlane_b32 s16, v163, 15
	v_readlane_b32 s17, v163, 16
	v_readlane_b32 s18, v163, 5
	v_readlane_b32 s19, v163, 6
	s_mul_i32 s4, s34, 0x1600000
	s_add_u32 s18, s18, s4
	s_addc_u32 s19, s19, 0
	s_add_u32 s18, s18, 0xb00000
	s_addc_u32 s19, s19, 0
	s_movk_i32 s42, 0x800
	v_and_b32_e32 v220, 63, v128
	v_lshrrev_b32_e32 v221, 6, v128
	v_and_b32_e32 v222, 15, v220
	v_lshrrev_b32_e32 v223, 4, v220
	v_readfirstlane_b32 s40, v221
	v_bfe_u32 v224, v222, 1, 3
	s_lshl_b32 s13, s40, 10
	s_and_b32 s36, s40, 1
	s_lshr_b32 s35, s40, 1
	v_xor_b32_e32 v225, v223, v224
	v_lshlrev_b32_e32 v225, 4, v225
	s_mul_i32 s4, s35, 0x50
	v_add_u32_e32 v226, s4, v222
	v_lshl_add_u32 v116, v226, 7, v225
	v_xor_b32_e32 v118, 64, v116
	s_lshl_b32 s4, s36, 6
	v_add_u32_e32 v227, s4, v222
	v_lshl_add_u32 v119, v227, 7, v225
	v_xor_b32_e32 v160, 64, v119
	v_and_b32_e32 v228, 7, v220
	v_lshrrev_b32_e32 v229, 3, v220
	v_xor_b32_e32 v230, v228, v223
	s_lshl_b32 s4, s36, 2
	v_xor_b32_e32 v230, s4, v230
	v_lshlrev_b32_e32 v230, 4, v230
	s_lshl_b32 s4, s40, 3
	v_add_u32_e32 v231, s4, v229
	v_mad_u32_u24 v161, v231, s42, v230
	v_bfe_u32 v232, v231, 2, 2
	v_and_b32_e32 v233, 3, v231
	v_lshrrev_b32_e32 v234, 4, v231
	v_lshl_add_u32 v232, v232, 3, v233
	s_movk_i32 s4, 0xb00
	v_mad_u32_u24 v232, v234, s4, v232
	v_mad_u32_u24 v165, v232, s42, v230
	v_mul_u32_u24_e32 v167, 0x1600, v226
	v_lshl_add_u32 v167, v223, 4, v167
	s_lshl_b32 s4, s36, 6
	v_add_u32_e32 v167, s4, v167
	s_movk_i32 s50, 0x580
	s_sub_u32 s51, s50, 1
	s_cmp_ge_u32 s10, s50
	s_cbranch_scc1 .Lggu1_done
	s_and_b32 s4, s10, 7
	s_lshl_b32 s4, s4, 3
	s_bfe_u32 s32, s10, 0x30003
	s_or_b32 s4, s4, s32
	s_mul_i32 s4, s4, 0x50000
	s_add_u32 s2, s16, s4
	s_addc_u32 s3, s17, 0
	s_lshr_b32 s4, s10, 6
	s_mul_i32 s4, s4, 0x40000
	s_add_u32 s6, s18, s4
	s_addc_u32 s7, s19, 0
	s_add_u32 m0, s13, 0x0
	s_nop 0
	global_load_lds_dwordx4 v161, s[2:3] sc1
	s_add_u32 m0, s13, 0x1000
	v_add_u32_e32 v166, 0x10000, v161
	global_load_lds_dwordx4 v166, s[2:3] sc1
	s_add_u32 m0, s13, 0x2000
	v_add_u32_e32 v166, 0x20000, v161
	global_load_lds_dwordx4 v166, s[2:3] sc1
	s_add_u32 m0, s13, 0x3000
	v_add_u32_e32 v166, 0x30000, v161
	global_load_lds_dwordx4 v166, s[2:3] sc1
	s_add_u32 m0, s13, 0x4000
	v_add_u32_e32 v166, 0x40000, v161
	global_load_lds_dwordx4 v166, s[2:3] sc1
	s_add_u32 m0, s13, 0x5000
	s_nop 0
	global_load_lds_dwordx4 v165, s[6:7]
	s_add_u32 m0, s13, 0x6000
	v_add_u32_e32 v166, 0x2000, v165
	global_load_lds_dwordx4 v166, s[6:7]
	s_add_u32 m0, s13, 0x7000
	v_add_u32_e32 v166, 0x10000, v165
	global_load_lds_dwordx4 v166, s[6:7]
	s_add_u32 m0, s13, 0x8000
	v_add_u32_e32 v166, 0x12000, v165
	global_load_lds_dwordx4 v166, s[6:7]
	s_add_u32 s24, s6, 0x20000
	s_addc_u32 s25, s7, 0
	s_add_u32 s2, s2, 0x80
	s_addc_u32 s3, s3, 0
	s_add_u32 s6, s6, 0x80
	s_addc_u32 s7, s7, 0
	s_mov_b32 s48, 0

.LBB0_1043:
	s_andn2_b64 vcc, exec, s[2:3]
	s_cbranch_vccnz .LBB0_1111
	v_readlane_b32 s10, v164, 0
	v_readlane_b32 s11, v162, 14
	s_mov_b32 s16, s76
	s_mov_b32 s17, s77
	v_readlane_b32 s18, v163, 7
	v_readlane_b32 s19, v163, 8
	s_mul_i32 s4, s34, 0xb00000
	s_add_u32 s18, s18, s4
	s_addc_u32 s19, s19, 0
	s_add_u32 s18, s18, 0x580000
	s_addc_u32 s19, s19, 0
	s_movk_i32 s42, 0x1600
	v_and_b32_e32 v220, 63, v128
	v_lshrrev_b32_e32 v221, 6, v128
	v_and_b32_e32 v222, 15, v220
	v_lshrrev_b32_e32 v223, 4, v220
	v_readfirstlane_b32 s40, v221
	v_bfe_u32 v224, v222, 1, 3
	s_lshl_b32 s13, s40, 10
	s_and_b32 s36, s40, 1
	s_lshr_b32 s35, s40, 1
	v_xor_b32_e32 v225, v223, v224
	v_lshlrev_b32_e32 v225, 4, v225
	s_mul_i32 s4, s35, 0x50
	v_add_u32_e32 v226, s4, v222
	v_lshl_add_u32 v204, v226, 7, v225
	v_xor_b32_e32 v205, 64, v204
	s_lshl_b32 s4, s36, 6
	v_add_u32_e32 v227, s4, v222
	v_lshl_add_u32 v206, v227, 7, v225
	v_xor_b32_e32 v207, 64, v206
	v_and_b32_e32 v228, 7, v220
	v_lshrrev_b32_e32 v229, 3, v220
	v_xor_b32_e32 v230, v228, v223
	s_lshl_b32 s4, s36, 2
	v_xor_b32_e32 v230, s4, v230
	v_lshlrev_b32_e32 v230, 4, v230
	s_lshl_b32 s4, s40, 3
	v_add_u32_e32 v231, s4, v229
	v_mad_u32_u24 v208, v231, s42, v230
	v_add_u32_e32 v209, 0x2c000, v208
	v_add_u32_e32 v210, 0x58000, v208
	v_add_u32_e32 v211, 0x84000, v208
	v_add_u32_e32 v212, 0xb0000, v208
	v_bfe_u32 v232, v231, 2, 2
	v_and_b32_e32 v233, 3, v231
	v_lshrrev_b32_e32 v234, 4, v231
	v_lshl_add_u32 v232, v232, 3, v233
	v_lshl_add_u32 v232, v234, 2, v232
	v_mad_u32_u24 v213, v232, s42, v230
	v_add_u32_e32 v214, 0x2c000, v213
	v_add_u32_e32 v215, 0x58000, v213
	v_add_u32_e32 v216, 0x84000, v213
	v_lshlrev_b32_e32 v217, 11, v226
	v_lshl_add_u32 v217, v223, 4, v217
	s_lshl_b32 s4, s36, 7
	v_add_u32_e32 v217, s4, v217
	s_cmp_ge_u32 s10, 0x200
	s_cbranch_scc1 .Lgdn1_done
	s_and_b32 s4, s10, 7
	s_lshl_b32 s4, s4, 3
	s_bfe_u32 s32, s10, 0x30003
	s_or_b32 s4, s4, s32
	s_mul_i32 s4, s4, 0xdc000
	s_add_u32 s2, s16, s4
	s_addc_u32 s3, s17, 0
	s_lshr_b32 s4, s10, 6
	s_mul_i32 s4, s4, 0xb0000
	s_add_u32 s6, s18, s4
	s_addc_u32 s7, s19, 0
	s_add_u32 m0, s13, 0x0
	s_nop 0
	global_load_lds_dwordx4 v208, s[2:3] sc1
	s_add_u32 m0, s13, 0x1000
	s_nop 0
	global_load_lds_dwordx4 v209, s[2:3] sc1
	s_add_u32 m0, s13, 0x2000
	s_nop 0
	global_load_lds_dwordx4 v210, s[2:3] sc1
	s_add_u32 m0, s13, 0x3000
	s_nop 0
	global_load_lds_dwordx4 v211, s[2:3] sc1
	s_add_u32 m0, s13, 0x4000
	s_nop 0
	global_load_lds_dwordx4 v212, s[2:3] sc1
	s_add_u32 m0, s13, 0x5000
	s_nop 0
	global_load_lds_dwordx4 v213, s[6:7]
	s_add_u32 m0, s13, 0x6000
	s_nop 0
	global_load_lds_dwordx4 v214, s[6:7]
	s_add_u32 m0, s13, 0x7000
	s_nop 0
	global_load_lds_dwordx4 v215, s[6:7]
	s_add_u32 m0, s13, 0x8000
	s_nop 0
	global_load_lds_dwordx4 v216, s[6:7]
	s_add_u32 s2, s2, 0x80
	s_addc_u32 s3, s3, 0
	s_add_u32 s6, s6, 0x80
	s_addc_u32 s7, s7, 0

.Lgdn1_done:
.LBB0_1061:
	v_readlane_b32 s2, v162, 36
	v_readlane_b32 s20, v162, 12
	s_add_i32 s35, s2, 13
	v_readlane_b32 s21, v162, 13
	s_cmp_ge_i32 s35, s21
	v_readlane_b32 s22, v162, 14
	v_readlane_b32 s23, v162, 15
	s_cbranch_scc1 .LBB0_1111
	s_waitcnt vmcnt(0)
	v_readlane_b32 s4, v163, 17
	v_readlane_b32 s5, v163, 18
	s_barrier
	v_readlane_b32 s21, v162, 62
	s_nop 1
	s_cmp_eq_u32 s21, 1
	s_cbranch_scc1 .Lxb10_noinv
	v_lshrrev_b32_e32 v0, 6, v128
	v_readfirstlane_b32 s20, v0
	s_cmp_lg_u32 s20, 1
	s_cbranch_scc1 .Lxb10_ninv
	buffer_inv sc1
